# v36: P5 state-scan stores write-through (sc1), full 1 KB lines per wave store
# speedup vs baseline: 1.0042x; 1.0011x over previous
; __global__ void __launch_bounds__(NTHREADS, 2) fwd_kernel(Params P) {
;     ...
;         for (int gid = bx * NTHREADS + tid; gid < 16 * 8192; gid += G * NTHREADS) {
;             const int bh = gid >> 13, e = gid & 8191, k = e >> 6;
;             f32x4 ds[15]; float dd[15];
; #pragma unroll
;             for (int j = 0; j < 15; ++j) { ds[j] = *((const f32x4*)(DS + (size_t)(bh * 15 + j) * 32768) + e); dd[j] = DV[(size_t)(bh * 15 + j) * 128 + k]; }
.LBB0_1248:
	v_ashrrev_i32_e32 v5, 13, v4
	v_and_b32_e32 v2, 0x1fff, v4
	v_lshrrev_b32_e32 v7, 4, v4
	v_mul_i32_i24_e32 v6, 15, v5
	v_lshlrev_b32_e32 v2, 4, v2
	v_mad_i32_i24 v8, v5, 15, 1
	v_mad_i32_i24 v10, v5, 15, 2
	v_mad_i32_i24 v12, v5, 15, 3
	v_mad_i32_i24 v14, v5, 15, 4
	v_mad_i32_i24 v16, v5, 15, 5
	v_mad_i32_i24 v18, v5, 15, 6
	v_mad_i32_i24 v20, v5, 15, 7
	v_mad_i32_i24 v22, v5, 15, 8
	v_mad_i32_i24 v24, v5, 15, 9
	v_mad_i32_i24 v26, v5, 15, 10
	v_mad_i32_i24 v28, v5, 15, 11
	v_mad_i32_i24 v30, v5, 15, 12
	v_mad_i32_i24 v32, v5, 15, 13
	v_mad_i32_i24 v34, v5, 15, 14
	v_lshl_add_u64 v[36:37], s[50:51], 0, v[2:3]
	v_and_b32_e32 v2, 0x1fc, v7
	v_ashrrev_i32_e32 v7, 31, v6
	v_ashrrev_i32_e32 v9, 31, v8
	v_ashrrev_i32_e32 v11, 31, v10
	v_ashrrev_i32_e32 v13, 31, v12
	v_ashrrev_i32_e32 v15, 31, v14
	v_ashrrev_i32_e32 v17, 31, v16
	v_ashrrev_i32_e32 v19, 31, v18
	v_ashrrev_i32_e32 v21, 31, v20
	v_ashrrev_i32_e32 v23, 31, v22
	v_ashrrev_i32_e32 v25, 31, v24
	v_ashrrev_i32_e32 v27, 31, v26
	v_ashrrev_i32_e32 v29, 31, v28
	v_ashrrev_i32_e32 v31, 31, v30
	v_ashrrev_i32_e32 v33, 31, v32
	v_ashrrev_i32_e32 v35, 31, v34
	v_lshl_add_u64 v[38:39], s[8:9], 0, v[2:3]
	v_lshlrev_b64 v[40:41], 17, v[6:7]
	v_lshlrev_b64 v[6:7], 9, v[6:7]
	v_lshlrev_b64 v[42:43], 17, v[8:9]
	v_lshlrev_b64 v[8:9], 9, v[8:9]
	v_lshlrev_b64 v[44:45], 17, v[10:11]
	v_lshlrev_b64 v[10:11], 9, v[10:11]
	v_lshlrev_b64 v[46:47], 17, v[12:13]
	v_lshlrev_b64 v[12:13], 9, v[12:13]
	v_lshlrev_b64 v[48:49], 17, v[14:15]
	v_lshlrev_b64 v[14:15], 9, v[14:15]
	v_lshlrev_b64 v[50:51], 17, v[16:17]
	v_lshlrev_b64 v[16:17], 9, v[16:17]
	v_lshlrev_b64 v[52:53], 17, v[18:19]
	v_lshlrev_b64 v[18:19], 9, v[18:19]
	v_lshlrev_b64 v[54:55], 17, v[20:21]
	v_lshlrev_b64 v[20:21], 9, v[20:21]
	v_lshlrev_b64 v[56:57], 17, v[22:23]
	v_lshlrev_b64 v[22:23], 9, v[22:23]
	v_lshlrev_b64 v[58:59], 17, v[24:25]
	v_lshlrev_b64 v[24:25], 9, v[24:25]
	v_lshlrev_b64 v[60:61], 17, v[26:27]
	v_lshlrev_b64 v[26:27], 9, v[26:27]
	v_lshlrev_b64 v[62:63], 17, v[28:29]
	v_lshlrev_b64 v[28:29], 9, v[28:29]
	v_lshlrev_b64 v[64:65], 17, v[30:31]
	v_lshlrev_b64 v[30:31], 9, v[30:31]
	v_lshlrev_b64 v[66:67], 17, v[32:33]
	v_lshlrev_b64 v[32:33], 9, v[32:33]
	v_lshlrev_b64 v[68:69], 17, v[34:35]
	v_lshlrev_b64 v[34:35], 9, v[34:35]
	v_lshl_add_u64 v[70:71], v[36:37], 0, v[40:41]
	v_lshl_add_u64 v[6:7], v[38:39], 0, v[6:7]
	v_lshl_add_u64 v[72:73], v[36:37], 0, v[42:43]
	v_lshl_add_u64 v[40:41], v[38:39], 0, v[8:9]
	v_lshl_add_u64 v[74:75], v[36:37], 0, v[44:45]
	v_lshl_add_u64 v[42:43], v[38:39], 0, v[10:11]
	v_lshl_add_u64 v[76:77], v[36:37], 0, v[46:47]
	v_lshl_add_u64 v[44:45], v[38:39], 0, v[12:13]
	v_lshl_add_u64 v[78:79], v[36:37], 0, v[48:49]
	v_lshl_add_u64 v[46:47], v[38:39], 0, v[14:15]
	v_lshl_add_u64 v[80:81], v[36:37], 0, v[50:51]
	v_lshl_add_u64 v[48:49], v[38:39], 0, v[16:17]
	v_lshl_add_u64 v[82:83], v[36:37], 0, v[52:53]
	v_lshl_add_u64 v[50:51], v[38:39], 0, v[18:19]
	v_lshl_add_u64 v[84:85], v[36:37], 0, v[54:55]
	v_lshl_add_u64 v[52:53], v[38:39], 0, v[20:21]
	v_lshl_add_u64 v[86:87], v[36:37], 0, v[56:57]
	v_lshl_add_u64 v[54:55], v[38:39], 0, v[22:23]
	v_lshl_add_u64 v[88:89], v[36:37], 0, v[58:59]
	v_lshl_add_u64 v[56:57], v[38:39], 0, v[24:25]
	v_lshl_add_u64 v[90:91], v[36:37], 0, v[60:61]
	v_lshl_add_u64 v[58:59], v[38:39], 0, v[26:27]
	v_lshl_add_u64 v[92:93], v[36:37], 0, v[62:63]
	v_lshl_add_u64 v[60:61], v[38:39], 0, v[28:29]
	v_lshl_add_u64 v[94:95], v[36:37], 0, v[64:65]
	v_lshl_add_u64 v[62:63], v[38:39], 0, v[30:31]
	v_lshl_add_u64 v[64:65], v[38:39], 0, v[32:33]
	v_lshl_add_u64 v[96:97], v[38:39], 0, v[34:35]
	v_lshl_add_u64 v[66:67], v[36:37], 0, v[66:67]
	v_lshl_add_u64 v[68:69], v[36:37], 0, v[68:69]
	global_load_dword v5, v[6:7], off
	s_nop 0
	global_load_dwordx4 v[6:9], v[70:71], off
	global_load_dwordx4 v[10:13], v[72:73], off
	global_load_dword v2, v[40:41], off
	global_load_dwordx4 v[14:17], v[74:75], off
	global_load_dword v98, v[42:43], off
	global_load_dwordx4 v[18:21], v[76:77], off
	global_load_dword v100, v[44:45], off
	global_load_dwordx4 v[22:25], v[78:79], off
	global_load_dword v102, v[46:47], off
	global_load_dwordx4 v[26:29], v[80:81], off
	global_load_dword v104, v[48:49], off
	global_load_dwordx4 v[30:33], v[82:83], off
	global_load_dword v106, v[50:51], off
	global_load_dwordx4 v[34:37], v[84:85], off
	global_load_dword v108, v[52:53], off
	global_load_dwordx4 v[38:41], v[86:87], off
	global_load_dword v110, v[54:55], off
	global_load_dwordx4 v[42:45], v[88:89], off
	global_load_dword v112, v[56:57], off
	global_load_dwordx4 v[46:49], v[90:91], off
	global_load_dword v114, v[58:59], off
	global_load_dwordx4 v[50:53], v[92:93], off
	global_load_dword v116, v[60:61], off
	s_nop 0
	global_load_dwordx4 v[54:57], v[94:95], off
	global_load_dword v118, v[62:63], off
	global_load_dwordx4 v[58:61], v[66:67], off
	global_load_dword v120, v[64:65], off
	s_nop 0
	global_load_dwordx4 v[62:65], v[68:69], off
	s_nop 0
	global_load_dword v96, v[96:97], off
	v_add_u32_e32 v4, s3, v4
	v_cmp_lt_i32_e32 vcc, s10, v4
	s_or_b64 s[6:7], vcc, s[6:7]
	s_waitcnt vmcnt(29)
; __global__ void __launch_bounds__(NTHREADS, 2) fwd_kernel(Params P) {
;     ...
;             f32x4 Sv = (f32x4){0.f, 0.f, 0.f, 0.f};
; #pragma unroll
;             for (int j = 0; j < 15; ++j) { Sv = Sv * dd[j] + ds[j]; *((f32x4*)(DS + (size_t)(bh * 15 + j) * 32768) + e) = Sv; }
;         }
	v_mul_f32_e32 v122, 0, v5
	s_waitcnt vmcnt(28)
	v_pk_add_f32 v[8:9], v[122:123], v[8:9] op_sel_hi:[0,1]
	v_pk_add_f32 v[6:7], v[122:123], v[6:7] op_sel_hi:[0,1]
	global_store_dwordx4 v[70:71], v[6:9], off sc1
	s_waitcnt vmcnt(27)
	s_nop 0
	v_pk_fma_f32 v[8:9], v[8:9], v[2:3], v[12:13] op_sel_hi:[1,0,1]
	v_pk_fma_f32 v[6:7], v[6:7], v[2:3], v[10:11] op_sel_hi:[1,0,1]
	global_store_dwordx4 v[72:73], v[6:9], off sc1
	s_waitcnt vmcnt(26)
	s_nop 0
	v_pk_fma_f32 v[8:9], v[8:9], v[98:99], v[16:17] op_sel_hi:[1,0,1]
	v_pk_fma_f32 v[6:7], v[6:7], v[98:99], v[14:15] op_sel_hi:[1,0,1]
	global_store_dwordx4 v[74:75], v[6:9], off sc1
	s_waitcnt vmcnt(25)
	s_nop 0
	v_pk_fma_f32 v[8:9], v[8:9], v[100:101], v[20:21] op_sel_hi:[1,0,1]
	v_pk_fma_f32 v[6:7], v[6:7], v[100:101], v[18:19] op_sel_hi:[1,0,1]
	global_store_dwordx4 v[76:77], v[6:9], off sc1
	s_waitcnt vmcnt(24)
	s_nop 0
	v_pk_fma_f32 v[8:9], v[8:9], v[102:103], v[24:25] op_sel_hi:[1,0,1]
	v_pk_fma_f32 v[6:7], v[6:7], v[102:103], v[22:23] op_sel_hi:[1,0,1]
	global_store_dwordx4 v[78:79], v[6:9], off sc1
	s_waitcnt vmcnt(23)
	s_nop 0
	v_pk_fma_f32 v[8:9], v[8:9], v[104:105], v[28:29] op_sel_hi:[1,0,1]
	v_pk_fma_f32 v[6:7], v[6:7], v[104:105], v[26:27] op_sel_hi:[1,0,1]
	global_store_dwordx4 v[80:81], v[6:9], off sc1
	s_waitcnt vmcnt(22)
	s_nop 0
	v_pk_fma_f32 v[8:9], v[8:9], v[106:107], v[32:33] op_sel_hi:[1,0,1]
	v_pk_fma_f32 v[6:7], v[6:7], v[106:107], v[30:31] op_sel_hi:[1,0,1]
	global_store_dwordx4 v[82:83], v[6:9], off sc1
	s_waitcnt vmcnt(21)
	s_nop 0
	v_pk_fma_f32 v[8:9], v[8:9], v[108:109], v[36:37] op_sel_hi:[1,0,1]
	v_pk_fma_f32 v[6:7], v[6:7], v[108:109], v[34:35] op_sel_hi:[1,0,1]
	global_store_dwordx4 v[84:85], v[6:9], off sc1
	s_waitcnt vmcnt(20)
	s_nop 0
	v_pk_fma_f32 v[8:9], v[8:9], v[110:111], v[40:41] op_sel_hi:[1,0,1]
	v_pk_fma_f32 v[6:7], v[6:7], v[110:111], v[38:39] op_sel_hi:[1,0,1]
	global_store_dwordx4 v[86:87], v[6:9], off sc1
	s_waitcnt vmcnt(19)
	s_nop 0
	v_pk_fma_f32 v[8:9], v[8:9], v[112:113], v[44:45] op_sel_hi:[1,0,1]
	v_pk_fma_f32 v[6:7], v[6:7], v[112:113], v[42:43] op_sel_hi:[1,0,1]
	global_store_dwordx4 v[88:89], v[6:9], off sc1
	s_waitcnt vmcnt(18)
	s_nop 0
	v_pk_fma_f32 v[8:9], v[8:9], v[114:115], v[48:49] op_sel_hi:[1,0,1]
	v_pk_fma_f32 v[6:7], v[6:7], v[114:115], v[46:47] op_sel_hi:[1,0,1]
	global_store_dwordx4 v[90:91], v[6:9], off sc1
	s_waitcnt vmcnt(17)
	s_nop 0
	v_pk_fma_f32 v[8:9], v[8:9], v[116:117], v[52:53] op_sel_hi:[1,0,1]
	v_pk_fma_f32 v[6:7], v[6:7], v[116:117], v[50:51] op_sel_hi:[1,0,1]
	global_store_dwordx4 v[92:93], v[6:9], off sc1
	s_waitcnt vmcnt(16)
	s_nop 0
	v_pk_fma_f32 v[8:9], v[8:9], v[118:119], v[56:57] op_sel_hi:[1,0,1]
	v_pk_fma_f32 v[6:7], v[6:7], v[118:119], v[54:55] op_sel_hi:[1,0,1]
	global_store_dwordx4 v[94:95], v[6:9], off sc1
	s_waitcnt vmcnt(15)
	s_nop 0
	v_pk_fma_f32 v[8:9], v[8:9], v[120:121], v[60:61] op_sel_hi:[1,0,1]
	v_pk_fma_f32 v[6:7], v[6:7], v[120:121], v[58:59] op_sel_hi:[1,0,1]
	global_store_dwordx4 v[66:67], v[6:9], off sc1
	s_waitcnt vmcnt(14)
	s_nop 0
	v_pk_fma_f32 v[8:9], v[8:9], v[96:97], v[64:65] op_sel_hi:[1,0,1]
	v_pk_fma_f32 v[6:7], v[6:7], v[96:97], v[62:63] op_sel_hi:[1,0,1]
	global_store_dwordx4 v[68:69], v[6:9], off sc1
	s_andn2_b64 exec, exec, s[6:7]
	s_cbranch_execnz .LBB0_1248
